# static priority raise for waves 4-7 also inside the R6 item loop
# speedup vs baseline: 1.0157x; 1.0157x over previous
.LBB0_113:
	s_add_u32 s62, s26, s0
	s_addc_u32 s63, s27, s1
	s_add_u32 s57, s62, 0x2b000000
	v_writelane_b32 v253, s8, 49
	s_addc_u32 s0, s63, 0
	v_writelane_b32 v253, s0, 51
	s_mul_i32 s0, s36, 3
	s_ashr_i32 s61, s60, 31
	v_writelane_b32 v253, s0, 52
	s_lshr_b32 s0, s61, 29
	s_add_i32 s70, s60, s0
	s_and_b32 s0, s70, -8
	s_sub_i32 s58, s60, s0
	s_cmp_lt_i32 s58, 0
	s_cselect_b64 s[0:1], -1, 0
	s_lshl_b32 s86, s36, 10
	s_add_i32 s46, s36, 1
	s_add_i32 s56, s36, -2
	s_add_u32 s76, s62, 0xc000000
	v_writelane_b32 v253, s0, 54
	s_addc_u32 s77, s63, 0
	s_mov_b32 s87, s73
	v_writelane_b32 v253, s1, 55
	s_mov_b64 s[0:1], -1
	s_mov_b64 s[52:53], 0
	s_cmp_lt_i32 s59, 5
	s_mov_b64 s[96:97], 0
	s_mov_b64 s[6:7], 0
	s_cbranch_scc1 .LBB0_545
	v_writelane_b32 v253, s68, 56
	v_writelane_b32 v253, s69, 58
	v_writelane_b32 v253, s86, 60
	s_lshl_b32 s78, s36, 24
	s_cmp_gt_i32 s59, 6
	v_writelane_b32 v253, s87, 61
	v_writelane_b32 v253, s70, 62
	s_cbranch_scc0 .LBB0_123
	s_mov_b32 s37, s73
	s_cmp_gt_i32 s59, 11
	s_cbranch_scc0 .LBB0_124
	s_cmp_gt_i32 s59, 12
	s_mov_b64 s[82:83], 0
	s_cbranch_scc0 .LBB0_127
	s_cmp_eq_u32 s59, 13
	s_mov_b64 s[6:7], -1
	s_cbranch_scc0 .LBB0_126
	s_mov_b64 s[0:1], 0
	v_mov_b32_e32 v2, v202
	v_readlane_b32 s66, v251, 0
	v_ashrrev_i32_e32 v8, 6, v2
	s_movk_i32 s4, 0x4000
	v_lshl_add_u32 v170, s66, 3, v8
	v_cmp_gt_i32_e32 vcc, s4, v170
	s_and_saveexec_b64 s[4:5], vcc
	s_cbranch_execz .LBB0_125
	s_add_u32 s64, s26, s0
	s_addc_u32 s65, s27, s1
	s_add_u32 s6, s64, 0x1b000000
	s_addc_u32 s7, s65, 0
	s_add_u32 s8, s64, 0x1f000000
	s_addc_u32 s9, s65, 0
	s_lshl_b32 s0, s78, 1
	s_add_u32 s0, s6, s0
	s_addc_u32 s1, s7, 0
	s_add_u32 s10, s0, 0xa000000
	s_addc_u32 s11, s1, 0
	s_add_u32 s30, s64, 0x29000000
	s_addc_u32 s31, s65, 0
	s_add_u32 s34, s64, 0x21000000
	s_mov_b32 s38, s46
	v_readlane_b32 s40, v253, 26
	s_addc_u32 s35, s65, 0
	s_lshl_b64 s[0:1], s[86:87], 2
	v_readlane_b32 s46, v253, 32
	v_readlane_b32 s50, v253, 36
	v_readlane_b32 s51, v253, 37
	s_mov_b32 s46, s38
	s_add_u32 s38, s50, s0
	v_readlane_b32 s52, v253, 38
	s_addc_u32 s39, s51, s1
	v_readlane_b32 s41, v253, 27
	v_readlane_b32 s53, v253, 39
	s_add_u32 s40, s52, s0
	v_readlane_b32 s42, v253, 28
	v_readlane_b32 s48, v253, 34
	s_addc_u32 s41, s53, s1
	v_readlane_b32 s43, v253, 29
	v_readlane_b32 s49, v253, 35
	s_add_u32 s42, s48, s0
	s_addc_u32 s43, s49, s1
	s_add_u32 s0, s64, 0x1d000000
	v_readlane_b32 s44, v253, 30
	s_addc_u32 s1, s65, 0
	v_readlane_b32 s45, v253, 31
	s_add_u32 s44, s64, 0x10000000
	s_addc_u32 s45, s65, 0
	v_ashrrev_i32_e32 v10, 2, v170
	s_add_u32 s64, s64, 0xe000000
	s_waitcnt lgkmcnt(0)
	v_and_b32_e32 v9, 63, v2
	s_waitcnt vmcnt(0)
	v_bfe_u32 v0, v2, 6, 2
	v_ashrrev_i32_e32 v11, 31, v10
	s_addc_u32 s65, s65, 0
	v_lshlrev_b64 v[12:13], 13, v[10:11]
	v_lshlrev_b32_e32 v11, 11, v0
	v_lshlrev_b32_e32 v16, 4, v9
	v_lshlrev_b32_e32 v28, 4, v0
	v_lshl_add_u64 v[14:15], s[64:65], 0, v[12:13]
	v_or_b32_e32 v0, v11, v16
	v_and_b32_e32 v3, 15, v2
	v_and_b32_e32 v17, 0xffffffc0, v170
	v_lshl_add_u64 v[14:15], v[14:15], 0, v[0:1]
	global_load_dwordx4 v[60:63], v[14:15], off
	global_load_dwordx4 v[64:67], v[14:15], off offset:1024
	v_or3_b32 v14, v3, v17, v28
	v_ashrrev_i32_e32 v15, 31, v14
	v_lshlrev_b32_e32 v10, 6, v10
	v_lshrrev_b32_e32 v2, 2, v2
	v_lshlrev_b64 v[14:15], 10, v[14:15]
	v_and_b32_e32 v10, 0x3c0, v10
	v_and_b32_e32 v2, 12, v2
	v_or3_b32 v14, v14, v10, v2
	v_lshl_add_u64 v[18:19], s[44:45], 0, v[12:13]
	v_lshl_add_u64 v[12:13], s[0:1], 0, v[12:13]
	v_mov_b32_e32 v17, v1
	v_lshlrev_b64 v[14:15], 1, v[14:15]
	v_lshl_add_u64 v[12:13], v[12:13], 0, v[16:17]
	v_lshl_add_u64 v[20:21], s[6:7], 0, v[14:15]
	global_load_dwordx4 v[48:51], v[12:13], off
	global_load_dwordx4 v[52:55], v[12:13], off offset:1024
	v_lshl_add_u64 v[22:23], s[8:9], 0, v[14:15]
	v_lshl_add_u64 v[24:25], s[10:11], 0, v[14:15]
	v_lshl_add_u64 v[26:27], s[30:31], 0, v[14:15]
	global_load_dwordx2 v[180:181], v[20:21], off
	global_load_dwordx2 v[182:183], v[22:23], off
	global_load_dwordx2 v[150:151], v[24:25], off
	global_load_dwordx2 v[164:165], v[26:27], off
	global_load_dwordx4 v[68:71], v[12:13], off offset:2048
	global_load_dwordx4 v[72:75], v[12:13], off offset:3072
	v_or_b32_e32 v20, 32, v14
	v_mov_b32_e32 v21, v15
	s_movk_i32 s67, 0x1000
	v_lshl_add_u64 v[22:23], s[6:7], 0, v[20:21]
	v_lshl_add_u64 v[24:25], s[8:9], 0, v[20:21]
	v_lshl_add_u64 v[26:27], s[10:11], 0, v[20:21]
	v_lshl_add_u64 v[20:21], s[30:31], 0, v[20:21]
	v_add_co_u32_e32 v12, vcc, s67, v12
	v_lshl_or_b32 v10, v9, 3, v11
	v_mov_b32_e32 v11, v1
	global_load_dwordx2 v[176:177], v[22:23], off
	global_load_dwordx2 v[178:179], v[24:25], off
	global_load_dwordx2 v[146:147], v[26:27], off
	global_load_dwordx2 v[148:149], v[20:21], off
	v_addc_co_u32_e32 v13, vcc, 0, v13, vcc
	v_or_b32_e32 v20, 64, v14
	v_mov_b32_e32 v21, v15
	v_or_b32_e32 v14, 0x60, v14
	v_lshl_add_u64 v[18:19], v[18:19], 0, v[10:11]
	global_load_dwordx4 v[76:79], v[12:13], off
	global_load_dwordx4 v[80:83], v[12:13], off offset:1024
	v_lshl_add_u64 v[22:23], s[6:7], 0, v[20:21]
	global_load_dwordx4 v[84:87], v[12:13], off offset:2048
	global_load_dwordx4 v[88:91], v[12:13], off offset:3072
	global_load_dwordx2 v[186:187], v[18:19], off
	global_load_dwordx2 v[184:185], v[18:19], off offset:512
	global_load_dwordx2 v[58:59], v[18:19], off offset:1024
	global_load_dwordx2 v[56:57], v[18:19], off offset:1536
	global_load_dwordx2 v[172:173], v[22:23], off
	v_lshl_add_u64 v[12:13], s[6:7], 0, v[14:15]
	global_load_dwordx2 v[166:167], v[12:13], off
	v_lshl_add_u64 v[12:13], s[8:9], 0, v[20:21]
	global_load_dwordx2 v[174:175], v[12:13], off
	v_lshl_add_u64 v[12:13], s[8:9], 0, v[14:15]
	global_load_dwordx2 v[168:169], v[12:13], off
	v_lshl_add_u64 v[12:13], s[10:11], 0, v[20:21]
	global_load_dwordx2 v[142:143], v[12:13], off
	v_lshl_add_u64 v[12:13], s[10:11], 0, v[14:15]
	global_load_dwordx2 v[126:127], v[12:13], off
	v_lshl_add_u64 v[12:13], s[30:31], 0, v[20:21]
	global_load_dwordx2 v[144:145], v[12:13], off
	v_lshl_add_u64 v[12:13], s[30:31], 0, v[14:15]
	global_load_dwordx2 v[130:131], v[12:13], off
	v_cmp_lt_i32_e32 vcc, v209, v210
	v_lshl_add_u64 v[92:93], s[64:65], 0, v[0:1]
	v_lshl_add_u64 v[94:95], s[44:45], 0, v[10:11]
	v_cndmask_b32_e32 v9, v208, v209, vcc
	v_cmp_lt_i32_e32 vcc, v211, v210
	v_lshlrev_b32_e32 v188, 2, v9
	v_lshl_add_u64 v[96:97], s[0:1], 0, v[16:17]
	v_cndmask_b32_e32 v9, v208, v211, vcc
	v_lshlrev_b32_e32 v189, 2, v9
	v_or_b32_e32 v190, v28, v3
	v_lshlrev_b32_e32 v0, 4, v8
	v_lshl_add_u32 v191, s66, 7, v0
	s_mov_b64 s[44:45], 0
	v_readlane_b32 s47, v253, 33
	v_readlane_b32 s54, v253, 40
	v_readlane_b32 s55, v253, 41
	s_waitcnt vmcnt(29)
	v_mov_b64_e32 v[8:9], v[60:61]
	s_waitcnt vmcnt(28)
	v_mov_b64_e32 v[12:13], v[64:65]
	v_mov_b64_e32 v[10:11], v[62:63]
	v_mov_b64_e32 v[14:15], v[66:67]
	s_waitcnt vmcnt(27)
	v_mov_b64_e32 v[16:17], v[48:49]
	s_waitcnt vmcnt(26)
	v_mov_b64_e32 v[20:21], v[52:53]
	v_mov_b64_e32 v[18:19], v[50:51]
	v_mov_b64_e32 v[22:23], v[54:55]
	s_waitcnt vmcnt(21)
	v_mov_b64_e32 v[24:25], v[68:69]
	s_waitcnt vmcnt(20)
	v_mov_b64_e32 v[28:29], v[72:73]
	v_mov_b64_e32 v[26:27], v[70:71]
	v_mov_b64_e32 v[30:31], v[74:75]
	v_mov_b64_e32 v[98:99], v[180:181]
	v_mov_b64_e32 v[100:101], v[182:183]
	v_mov_b64_e32 v[102:103], v[150:151]
	v_mov_b64_e32 v[104:105], v[164:165]
	s_waitcnt vmcnt(19)
	v_mov_b64_e32 v[106:107], v[176:177]
	s_waitcnt vmcnt(18)
	v_mov_b64_e32 v[108:109], v[178:179]
	s_waitcnt vmcnt(17)
	v_mov_b64_e32 v[110:111], v[146:147]
	s_waitcnt vmcnt(16)
	v_mov_b64_e32 v[112:113], v[148:149]
	s_waitcnt vmcnt(13)
	v_mov_b64_e32 v[40:41], v[84:85]
	s_waitcnt vmcnt(12)
	v_mov_b64_e32 v[44:45], v[88:89]
	v_mov_b64_e32 v[42:43], v[86:87]
	v_mov_b64_e32 v[32:33], v[76:77]
	v_mov_b64_e32 v[36:37], v[80:81]
	v_mov_b64_e32 v[34:35], v[78:79]
	v_mov_b64_e32 v[38:39], v[82:83]
	v_mov_b64_e32 v[46:47], v[90:91]
	s_waitcnt vmcnt(11)
	v_mov_b64_e32 v[114:115], v[186:187]
	s_waitcnt vmcnt(10)
	v_mov_b64_e32 v[116:117], v[184:185]
	s_waitcnt vmcnt(9)
	v_mov_b64_e32 v[120:121], v[58:59]
	s_waitcnt vmcnt(8)
	v_mov_b64_e32 v[122:123], v[56:57]
	s_waitcnt vmcnt(7)
	v_mov_b64_e32 v[118:119], v[172:173]
	s_waitcnt vmcnt(6)
	v_mov_b64_e32 v[134:135], v[166:167]
	s_waitcnt vmcnt(5)
	v_mov_b64_e32 v[124:125], v[174:175]
	s_waitcnt vmcnt(4)
	v_mov_b64_e32 v[136:137], v[168:169]
	s_waitcnt vmcnt(3)
	v_mov_b64_e32 v[128:129], v[142:143]
	s_waitcnt vmcnt(2)
	v_mov_b64_e32 v[138:139], v[126:127]
	s_waitcnt vmcnt(1)
	v_mov_b64_e32 v[132:133], v[144:145]
	s_waitcnt vmcnt(0)
	v_mov_b64_e32 v[140:141], v[130:131]
	v_readfirstlane_b32 s101, v202
	s_nop 3
	s_lshr_b32 s101, s101, 6
	s_cmp_ge_u32 s101, 4
	s_cbranch_scc0 .Lr6_prio_done
	s_setprio 1
.Lr6_prio_done:
	s_branch .LBB0_121
.LBB0_120:
	s_or_b64 exec, exec, s[0:1]
	v_and_b32_e32 v0, 0xffffffc0, v170
	v_and_b32_e32 v152, 48, v191
	v_or3_b32 v170, v0, v152, v3
	v_lshlrev_b32_e32 v152, 16, v186
	v_and_b32_e32 v153, 0xffff0000, v186
	v_lshlrev_b32_e32 v154, 16, v187
	v_and_b32_e32 v155, 0xffff0000, v187
	v_lshlrev_b32_e32 v160, 16, v184
	v_and_b32_e32 v161, 0xffff0000, v184
	v_mfma_f32_16x16x32_bf16 v[48:51], v[48:51], v[60:63], v[152:155]
	v_lshlrev_b32_e32 v162, 16, v185
	v_and_b32_e32 v163, 0xffff0000, v185
	v_lshlrev_b32_e32 v184, 16, v58
	v_and_b32_e32 v185, 0xffff0000, v58
	v_lshlrev_b32_e32 v186, 16, v59
	v_and_b32_e32 v187, 0xffff0000, v59
	v_lshlrev_b32_e32 v194, 16, v56
	v_and_b32_e32 v195, 0xffff0000, v56
	v_lshlrev_b32_e32 v196, 16, v57
	v_and_b32_e32 v197, 0xffff0000, v57
	v_mfma_f32_16x16x32_bf16 v[56:59], v[52:55], v[64:67], v[48:51]
	s_movk_i32 s0, 0x3c0
	v_and_or_b32 v0, v191, s0, v2
	v_ashrrev_i32_e32 v171, 31, v170
	v_mfma_f32_16x16x32_bf16 v[48:51], v[68:71], v[60:63], v[160:163]
	v_lshlrev_b32_e32 v71, 2, v0
	v_lshlrev_b32_e32 v68, 16, v180
	v_and_b32_e32 v69, 0xffff0000, v180
	v_mfma_f32_16x16x32_bf16 v[52:55], v[72:75], v[64:67], v[48:51]
	v_lshlrev_b32_e32 v73, 16, v182
	v_and_b32_e32 v74, 0xffff0000, v182
	v_mul_f32_e32 v68, v68, v73
	v_mfma_f32_16x16x32_bf16 v[48:51], v[76:79], v[60:63], v[184:187]
	v_add_f32_e32 v77, 0, v56
	v_lshlrev_b32_e32 v70, 16, v181
	v_lshlrev_b32_e32 v75, 16, v183
	v_mfma_f32_16x16x32_bf16 v[60:63], v[84:87], v[60:63], v[194:197]
	v_and_b32_e32 v72, 0xffff0000, v181
	v_and_b32_e32 v76, 0xffff0000, v183
	v_lshlrev_b32_e32 v0, 1, v0
	v_mfma_f32_16x16x32_bf16 v[48:51], v[80:83], v[64:67], v[48:51]
	v_lshlrev_b32_e32 v80, 16, v151
	v_and_b32_e32 v81, 0xffff0000, v151
	v_lshlrev_b32_e32 v82, 16, v165
	v_mfma_f32_16x16x32_bf16 v[60:63], v[88:91], v[64:67], v[60:63]
	v_mov_b64_e32 v[64:65], v[216:217]
	v_mov_b64_e32 v[66:67], v[218:219]
	v_and_b32_e32 v83, 0xffff0000, v165
	v_lshlrev_b32_e32 v90, 16, v150
	v_and_b32_e32 v91, 0xffff0000, v150
	v_lshlrev_b32_e32 v150, 16, v164
	v_and_b32_e32 v151, 0xffff0000, v164
	v_lshlrev_b32_e32 v164, 16, v146
	v_and_b32_e32 v165, 0xffff0000, v146
	v_lshlrev_b32_e32 v146, 16, v148
	s_mov_b32 s0, 0x800000
	v_add_u32_e32 v191, s81, v191
	s_waitcnt vmcnt(9)
	v_mov_b64_e32 v[186:187], v[114:115]
	s_waitcnt vmcnt(8)
	v_mov_b64_e32 v[184:185], v[116:117]
	v_mov_b64_e32 v[180:181], v[98:99]
	v_mov_b64_e32 v[182:183], v[100:101]
	v_fma_f32 v73, v68, v64, 0
	v_add_f32_e32 v64, v57, v77
	v_mul_f32_e32 v68, v69, v74
	v_fmac_f32_e32 v73, v68, v65
	v_add_f32_e32 v64, v58, v64
	v_mul_f32_e32 v65, v70, v75
	v_fmac_f32_e32 v73, v65, v66
	v_add_f32_e32 v68, v59, v64
	v_mul_f32_e32 v64, v72, v76
	v_fmac_f32_e32 v73, v64, v67
	v_mov_b64_e32 v[64:65], v[220:221]
	v_mov_b64_e32 v[66:67], v[222:223]
	v_lshlrev_b32_e32 v69, 16, v176
	v_lshlrev_b32_e32 v72, 16, v178
	v_add_f32_e32 v68, v52, v68
	v_mul_f32_e32 v69, v69, v72
	v_and_b32_e32 v70, 0xffff0000, v176
	v_and_b32_e32 v74, 0xffff0000, v178
	v_lshlrev_b32_e32 v72, 16, v174
	v_fmac_f32_e32 v73, v69, v64
	v_add_f32_e32 v64, v53, v68
	v_mul_f32_e32 v68, v70, v74
	v_add_f32_e32 v64, v54, v64
	v_fmac_f32_e32 v73, v68, v65
	v_add_f32_e32 v70, v55, v64
	v_and_b32_e32 v65, 0xffff0000, v177
	v_lshlrev_b32_e32 v64, 16, v177
	v_and_b32_e32 v69, 0xffff0000, v179
	v_lshlrev_b32_e32 v68, 16, v179
	v_pk_mul_f32 v[64:65], v[64:65], v[68:69]
	v_add_f32_e32 v68, v48, v70
	v_pk_mul_f32 v[64:65], v[64:65], v[66:67]
	v_add_f32_e32 v70, v49, v68
	v_add_f32_e32 v64, v64, v73
	v_add_f32_e32 v74, v65, v64
	v_mov_b64_e32 v[64:65], v[224:225]
	v_mov_b64_e32 v[66:67], v[226:227]
	v_and_b32_e32 v69, 0xffff0000, v172
	v_lshlrev_b32_e32 v68, 16, v172
	v_and_b32_e32 v73, 0xffff0000, v174
	v_pk_mul_f32 v[68:69], v[68:69], v[72:73]
	v_and_b32_e32 v73, 0xffff0000, v168
	v_mov_b64_e32 v[176:177], v[106:107]
	v_mov_b64_e32 v[178:179], v[108:109]
	v_pk_mul_f32 v[64:65], v[68:69], v[64:65]
	s_nop 0
	v_add_f32_e32 v64, v64, v74
	v_add_f32_e32 v72, v65, v64
	v_add_f32_e32 v64, v50, v70
	v_add_f32_e32 v70, v51, v64
	v_and_b32_e32 v65, 0xffff0000, v173
	v_lshlrev_b32_e32 v64, 16, v173
	v_and_b32_e32 v69, 0xffff0000, v175
	v_lshlrev_b32_e32 v68, 16, v175
	v_pk_mul_f32 v[64:65], v[64:65], v[68:69]
	v_add_f32_e32 v68, v60, v70
	v_pk_mul_f32 v[64:65], v[64:65], v[66:67]
	v_add_f32_e32 v70, v61, v68
	v_add_f32_e32 v64, v64, v72
	v_add_f32_e32 v74, v65, v64
	v_mov_b64_e32 v[64:65], v[228:229]
	v_mov_b64_e32 v[66:67], v[230:231]
	v_and_b32_e32 v69, 0xffff0000, v166
	v_lshlrev_b32_e32 v68, 16, v166
	v_lshlrev_b32_e32 v72, 16, v168
	v_pk_mul_f32 v[68:69], v[68:69], v[72:73]
	v_mov_b64_e32 v[172:173], v[118:119]
	v_mov_b64_e32 v[174:175], v[124:125]
	v_pk_mul_f32 v[64:65], v[68:69], v[64:65]
	s_nop 0
	v_add_f32_e32 v64, v64, v74
	v_add_f32_e32 v72, v65, v64
	v_add_f32_e32 v64, v62, v70
	v_add_f32_e32 v70, v63, v64
	v_and_b32_e32 v65, 0xffff0000, v167
	v_lshlrev_b32_e32 v64, 16, v167
	v_and_b32_e32 v69, 0xffff0000, v169
	v_lshlrev_b32_e32 v68, 16, v169
	v_pk_mul_f32 v[64:65], v[64:65], v[68:69]
	s_nop 0
	v_pk_mul_f32 v[64:65], v[64:65], v[66:67]
	s_nop 0
	v_add_f32_e32 v64, v64, v72
	v_add_f32_e32 v64, v65, v64
	ds_bpermute_b32 v65, v188, v70
	s_waitcnt lgkmcnt(0)
	v_add_f32_e32 v65, v70, v65
	ds_bpermute_b32 v66, v189, v65
	s_waitcnt lgkmcnt(0)
	v_add_f32_e32 v65, v65, v66
	ds_bpermute_b32 v66, v188, v64
	v_mul_f32_e32 v78, 0x3c800000, v65
	v_pk_add_f32 v[72:73], v[60:61], v[78:79] op_sel_hi:[1,0] neg_lo:[0,1] neg_hi:[0,1]
	v_lshlrev_b64 v[60:61], 11, v[170:171]
	v_pk_add_f32 v[68:69], v[62:63], v[78:79] op_sel_hi:[1,0] neg_lo:[0,1] neg_hi:[0,1]
	s_waitcnt lgkmcnt(0)
	v_add_f32_e32 v64, v64, v66
	ds_bpermute_b32 v66, v189, v64
	v_lshl_add_u64 v[84:85], s[34:35], 0, v[60:61]
	v_pk_add_f32 v[152:153], v[56:57], v[78:79] op_sel_hi:[1,0] neg_lo:[0,1] neg_hi:[0,1]
	v_pk_add_f32 v[86:87], v[58:59], v[78:79] op_sel_hi:[1,0] neg_lo:[0,1] neg_hi:[0,1]
	v_pk_mul_f32 v[154:155], v[152:153], v[152:153]
	s_waitcnt lgkmcnt(0)
	v_add_f32_e32 v70, v64, v66
	v_mov_b64_e32 v[60:61], v[232:233]
	v_mov_b64_e32 v[62:63], v[234:235]
	v_mov_b64_e32 v[64:65], v[236:237]
	v_mov_b64_e32 v[66:67], v[238:239]
	v_pk_mul_f32 v[88:89], v[86:87], v[86:87]
	v_lshl_add_u64 v[56:57], v[84:85], 0, v[0:1]
	v_add_f32_e32 v0, v154, v155
	v_lshlrev_b32_e32 v58, 16, v147
	v_and_b32_e32 v59, 0xffff0000, v147
	v_lshlrev_b32_e32 v84, 16, v149
	v_and_b32_e32 v85, 0xffff0000, v149
	v_and_b32_e32 v147, 0xffff0000, v148
	v_pk_add_f32 v[148:149], v[52:53], v[78:79] op_sel_hi:[1,0] neg_lo:[0,1] neg_hi:[0,1]
	v_add_f32_e32 v0, v88, v0
	v_pk_mul_f32 v[166:167], v[148:149], v[148:149]
	v_add_f32_e32 v0, v89, v0
	v_pk_add_f32 v[160:161], v[54:55], v[78:79] op_sel_hi:[1,0] neg_lo:[0,1] neg_hi:[0,1]
	v_add_f32_e32 v0, v166, v0
	v_pk_mul_f32 v[162:163], v[160:161], v[160:161]
	v_add_f32_e32 v0, v167, v0
	v_pk_add_f32 v[168:169], v[50:51], v[78:79] op_sel_hi:[1,0] neg_lo:[0,1] neg_hi:[0,1]
	v_pk_add_f32 v[78:79], v[48:49], v[78:79] op_sel_hi:[1,0] neg_lo:[0,1] neg_hi:[0,1]
	v_add_f32_e32 v0, v162, v0
	v_pk_mul_f32 v[48:49], v[78:79], v[78:79]
	v_add_f32_e32 v0, v163, v0
	v_add_f32_e32 v0, v48, v0
	v_pk_mul_f32 v[50:51], v[168:169], v[168:169]
	v_add_f32_e32 v0, v49, v0
	v_add_f32_e32 v0, v50, v0
	v_pk_mul_f32 v[74:75], v[72:73], v[72:73]
	v_add_f32_e32 v0, v51, v0
	v_add_f32_e32 v0, v74, v0
	v_pk_mul_f32 v[76:77], v[68:69], v[68:69]
	v_add_f32_e32 v0, v75, v0
	v_add_f32_e32 v0, v76, v0
	v_add_f32_e32 v0, v77, v0
	ds_bpermute_b32 v48, v188, v0
	v_lshlrev_b32_e32 v54, 16, v143
	v_and_b32_e32 v55, 0xffff0000, v143
	v_lshlrev_b32_e32 v170, 16, v142
	v_and_b32_e32 v171, 0xffff0000, v142
	s_waitcnt lgkmcnt(0)
	v_add_f32_e32 v0, v0, v48
	ds_bpermute_b32 v48, v189, v0
	v_lshlrev_b32_e32 v52, 16, v145
	v_and_b32_e32 v53, 0xffff0000, v145
	v_lshlrev_b32_e32 v142, 16, v144
	v_and_b32_e32 v143, 0xffff0000, v144
	s_waitcnt lgkmcnt(0)
	v_add_f32_e32 v0, v0, v48
	v_fmamk_f32 v0, v0, 0x3c800000, v214
	v_cmp_gt_f32_e32 vcc, s0, v0
	v_mul_f32_e32 v48, 0x4b800000, v0
	s_waitcnt vmcnt(3)
	v_mov_b64_e32 v[166:167], v[134:135]
	v_cndmask_b32_e32 v0, v0, v48, vcc
	v_rsq_f32_e32 v0, v0
	v_mov_b64_e32 v[144:145], v[132:133]
	v_mul_f32_e32 v48, 0x45800000, v0
	v_cndmask_b32_e32 v0, v0, v48, vcc
	v_pk_mul_f32 v[48:49], v[152:153], v[0:1] op_sel_hi:[1,0]
	v_pk_mul_f32 v[50:51], v[86:87], v[0:1] op_sel_hi:[1,0]
	v_pk_fma_f32 v[48:49], v[60:61], v[48:49], v[64:65]
	v_pk_fma_f32 v[50:51], v[62:63], v[50:51], v[66:67]
	v_pk_fma_f32 v[48:49], v[70:71], v[90:91], v[48:49] op_sel_hi:[0,1,1]
	v_pk_fma_f32 v[50:51], v[70:71], v[80:81], v[50:51] op_sel_hi:[0,1,1]
	v_pk_mul_f32 v[48:49], v[48:49], v[150:151]
	v_pk_mul_f32 v[50:51], v[50:51], v[82:83]
	v_cvt_pk_bf16_f32 v48, v48, v49
	v_cvt_pk_bf16_f32 v49, v50, v51
	global_store_dwordx2 v[56:57], v[48:49], off
	v_mov_b64_e32 v[48:49], v[240:241]
	v_mov_b64_e32 v[50:51], v[242:243]
	s_nop 0
	v_mov_b64_e32 v[60:61], v[244:245]
	v_mov_b64_e32 v[62:63], v[246:247]
	v_pk_mul_f32 v[64:65], v[148:149], v[0:1] op_sel_hi:[1,0]
	v_mov_b64_e32 v[82:83], v[38:39]
	v_mov_b64_e32 v[90:91], v[46:47]
	v_mov_b64_e32 v[80:81], v[36:37]
	v_mov_b64_e32 v[88:89], v[44:45]
	v_mov_b64_e32 v[150:151], v[102:103]
	v_mov_b64_e32 v[148:149], v[112:113]
	v_pk_fma_f32 v[48:49], v[48:49], v[64:65], v[60:61]
	v_pk_mul_f32 v[60:61], v[160:161], v[0:1] op_sel_hi:[1,0]
	v_pk_fma_f32 v[48:49], v[70:71], v[164:165], v[48:49] op_sel_hi:[0,1,1]
	v_pk_fma_f32 v[50:51], v[50:51], v[60:61], v[62:63]
	v_pk_mul_f32 v[48:49], v[48:49], v[146:147]
	v_pk_fma_f32 v[50:51], v[70:71], v[58:59], v[50:51] op_sel_hi:[0,1,1]
	v_pk_mul_f32 v[50:51], v[50:51], v[84:85]
	v_cvt_pk_bf16_f32 v48, v48, v49
	v_cvt_pk_bf16_f32 v49, v50, v51
	global_store_dwordx2 v[56:57], v[48:49], off offset:32
	global_load_dwordx4 v[48:51], v71, s[38:39] offset:128
	s_nop 0
	global_load_dwordx4 v[58:61], v71, s[40:41] offset:128
	v_pk_mul_f32 v[62:63], v[78:79], v[0:1] op_sel_hi:[1,0]
	v_mov_b64_e32 v[66:67], v[14:15]
	v_mov_b64_e32 v[78:79], v[34:35]
	v_mov_b64_e32 v[86:87], v[42:43]
	v_mov_b64_e32 v[64:65], v[12:13]
	v_mov_b64_e32 v[76:77], v[32:33]
	v_mov_b64_e32 v[84:85], v[40:41]
	v_mov_b64_e32 v[146:147], v[110:111]
	v_mov_b64_e32 v[164:165], v[104:105]
	s_waitcnt vmcnt(0)
	v_pk_fma_f32 v[48:49], v[48:49], v[62:63], v[58:59]
	v_pk_mul_f32 v[58:59], v[168:169], v[0:1] op_sel_hi:[1,0]
	v_pk_fma_f32 v[48:49], v[70:71], v[170:171], v[48:49] op_sel_hi:[0,1,1]
	v_pk_fma_f32 v[50:51], v[50:51], v[58:59], v[60:61]
	v_pk_mul_f32 v[48:49], v[48:49], v[142:143]
	v_pk_fma_f32 v[50:51], v[70:71], v[54:55], v[50:51] op_sel_hi:[0,1,1]
	v_pk_mul_f32 v[50:51], v[50:51], v[52:53]
	v_cvt_pk_bf16_f32 v48, v48, v49
	v_cvt_pk_bf16_f32 v49, v50, v51
	global_store_dwordx2 v[56:57], v[48:49], off offset:64
	global_load_dwordx4 v[48:51], v71, s[38:39] offset:192
	s_nop 0
	global_load_dwordx4 v[52:55], v71, s[40:41] offset:192
	v_pk_mul_f32 v[62:63], v[72:73], v[0:1] op_sel_hi:[1,0]
	v_lshlrev_b32_e32 v58, 16, v126
	v_and_b32_e32 v59, 0xffff0000, v126
	v_lshlrev_b32_e32 v60, 16, v130
	v_and_b32_e32 v61, 0xffff0000, v130
	v_mov_b64_e32 v[74:75], v[30:31]
	v_mov_b64_e32 v[72:73], v[28:29]
	v_mov_b64_e32 v[168:169], v[136:137]
	v_mov_b64_e32 v[142:143], v[128:129]
	v_mov_b32_e32 v170, v192
	s_waitcnt vmcnt(0)
	v_pk_fma_f32 v[48:49], v[48:49], v[62:63], v[52:53]
	s_nop 0
	v_pk_fma_f32 v[48:49], v[70:71], v[58:59], v[48:49] op_sel_hi:[0,1,1]
	v_pk_mul_f32 v[48:49], v[48:49], v[60:61]
	v_pk_mul_f32 v[60:61], v[68:69], v[0:1] op_sel_hi:[1,0]
	v_lshlrev_b32_e32 v52, 16, v127
	v_and_b32_e32 v53, 0xffff0000, v127
	v_pk_fma_f32 v[50:51], v[50:51], v[60:61], v[54:55]
	v_lshlrev_b32_e32 v58, 16, v131
	v_and_b32_e32 v59, 0xffff0000, v131
	v_pk_fma_f32 v[50:51], v[70:71], v[52:53], v[50:51] op_sel_hi:[0,1,1]
	v_pk_mul_f32 v[50:51], v[50:51], v[58:59]
	v_cvt_pk_bf16_f32 v48, v48, v49
	v_cvt_pk_bf16_f32 v49, v50, v51
	global_store_dwordx2 v[56:57], v[48:49], off offset:96
	v_mov_b64_e32 v[62:63], v[10:11]
	v_mov_b64_e32 v[50:51], v[18:19]
	v_mov_b64_e32 v[54:55], v[22:23]
	v_mov_b64_e32 v[70:71], v[26:27]
	v_mov_b64_e32 v[60:61], v[8:9]
	v_mov_b64_e32 v[48:49], v[16:17]
	v_mov_b64_e32 v[52:53], v[20:21]
	v_mov_b64_e32 v[68:69], v[24:25]
	v_mov_b64_e32 v[58:59], v[120:121]
	v_mov_b64_e32 v[56:57], v[122:123]
	v_mov_b64_e32 v[126:127], v[138:139]
	v_mov_b64_e32 v[130:131], v[140:141]
	s_andn2_b64 exec, exec, s[44:45]
	s_cbranch_execz .LBB0_125

.LBB0_125:
	s_setprio 0
	s_or_b64 exec, exec, s[4:5]
	s_mov_b64 s[6:7], 0
